# norm1/norm2 rows: wave all-reduce of the sum of squares through v_permlane32/16_swap and DPP (row_ror, half_mirror, quad_perm) instead of six ds_bpermute round trips
# baseline (speedup 1.0000x reference)
; DI unsigned pack2(float lo, float hi) { f32x2 v; v.x = lo; v.y = hi; return __builtin_bit_cast(unsigned, __builtin_convertvector(v, hwbf2)); }
; DI float wave_sum(float v) {
; #pragma unroll
;   for (int o = 32; o > 0; o >>= 1) v += __shfl_xor(v, o);
;   return v;
; }
; DI void norm_rows(KP p, int l, int which, int u, const float* xlat, const float* xctx) {
;     ...
;   f32x4 v[4];
;   float ss = 0;
; #pragma unroll
;   for (int j = 0; j < 4; ++j) {
;     v[j] = *(const f32x4*)(xr + 4 * (lane + 64 * j));
;     ss += v[j].x * v[j].x + v[j].y * v[j].y + v[j].z * v[j].z + v[j].w * v[j].w;
;   }
;   ss = wave_sum(ss);
;   const float rstd = rsqrtf(ss * (1.f / 1024.f) + EPS);
;   u16* H = (u16*)(p->ws + OFF_H) + (size_t)row * 1024;
; #pragma unroll
;   for (int j = 0; j < 4; ++j) {
;     const int c0 = 4 * (lane + 64 * j);
;     f32x4 gg = *(const f32x4*)(g + c0), sh = *(const f32x4*)(mods + c0), sc = *(const f32x4*)(mods + 1024 + c0);
;     float o0 = v[j].x * rstd * gg.x * (1.f + sc.x) + sh.x;
;     float o1 = v[j].y * rstd * gg.y * (1.f + sc.y) + sh.y;
;     float o2 = v[j].z * rstd * gg.z * (1.f + sc.z) + sh.z;
;     float o3 = v[j].w * rstd * gg.w * (1.f + sc.w) + sh.w;
;     *(u32x2*)(H + c0) = mk2(pack2(o0, o1), pack2(o2, o3));
;   }
.LBB0_124:
	s_or_b64 exec, exec, s[8:9]
	v_lshlrev_b32_e32 v4, 2, v4
	v_and_b32_e32 v38, 0xfc, v4
	v_lshlrev_b32_e32 v198, 2, v38
	v_lshl_add_u64 v[2:3], v[2:3], 0, v[198:199]
	s_load_dwordx2 s[10:11], s[18:19], 0x130
	s_load_dwordx2 s[8:9], s[18:19], 0x30
	global_load_dwordx4 v[14:17], v[2:3], off
	global_load_dwordx4 v[10:13], v[2:3], off offset:1024
	v_min_i32_e32 v5, 0x4000, v20
	v_ashrrev_i32_e32 v5, 12, v5
	s_mul_i32 s2, s76, 5
	v_add_u32_e32 v5, s2, v5
	v_mul_hi_i32_i24_e32 v19, 0x6000, v5
	v_mul_i32_i24_e32 v18, 0x6000, v5
	s_lshl_b64 s[2:3], s[74:75], 2
	s_waitcnt lgkmcnt(0)
	s_add_u32 s8, s8, s2
	s_mov_b32 s2, 0x800000
	s_addc_u32 s9, s9, s3
	global_load_dwordx4 v[132:135], v[2:3], off offset:2048
	s_nop 0
	global_load_dwordx4 v[136:139], v[2:3], off offset:3072
	global_load_dwordx4 v[140:143], v198, s[8:9]
	v_lshl_add_u64 v[144:145], s[10:11], 0, v[18:19]
	v_lshl_add_u64 v[146:147], v[144:145], 0, v[198:199]
	s_nop 0
	s_mov_b64 s[82:83], 0xe821000
	v_lshl_add_u64 v[148:149], v[144:145], 0, s[82:83]
	s_mov_b64 s[84:85], 0xe820000
	v_lshl_add_u64 v[150:151], v[146:147], 0, s[84:85]
	s_mov_b32 s86, 0xe820000
	v_add_co_u32_e32 v152, vcc, s86, v146
	v_lshl_add_u64 v[154:155], v[148:149], 0, v[198:199]
	s_nop 0
	v_addc_co_u32_e32 v153, vcc, 0, v147, vcc
	global_load_dwordx4 v[156:159], v[152:153], off
	global_load_dwordx4 v[160:163], v[154:155], off
	v_or_b32_e32 v164, 0x400, v198
	v_mov_b32_e32 v165, v199
	v_lshl_add_u64 v[166:167], v[148:149], 0, v[164:165]
	global_load_dwordx4 v[168:171], v198, s[8:9] offset:1024
	global_load_dwordx4 v[172:175], v[150:151], off offset:1024
	global_load_dwordx4 v[176:179], v[166:167], off
	v_or_b32_e32 v180, 0x800, v198
	v_mov_b32_e32 v181, v199
	v_lshl_add_u64 v[182:183], v[148:149], 0, v[180:181]
	global_load_dwordx4 v[184:187], v198, s[8:9] offset:2048
	global_load_dwordx4 v[188:191], v[150:151], off offset:2048
	global_load_dwordx4 v[192:195], v[182:183], off
	global_load_dwordx4 v[200:203], v198, s[8:9] offset:3072
	s_nop 0
	global_load_dwordx4 v[204:207], v[150:151], off offset:3072
	v_or_b32_e32 v196, 0xc00, v198
	v_mov_b32_e32 v197, v199
	v_lshl_add_u64 v[208:209], v[148:149], 0, v[196:197]
	global_load_dwordx4 v[224:227], v[208:209], off
	s_waitcnt vmcnt(0)
	v_lshlrev_b64 v[20:21], 11, v[20:21]
	v_mov_b32_e32 v6, v15
	v_mov_b32_e32 v7, v11
	v_mov_b32_e32 v4, v14
	v_mov_b32_e32 v5, v10
	v_pk_mul_f32 v[6:7], v[6:7], v[6:7]
	s_nop 0
	v_pk_fma_f32 v[4:5], v[4:5], v[4:5], v[6:7]
	v_mov_b32_e32 v6, v16
	v_mov_b32_e32 v7, v12
	v_pk_fma_f32 v[4:5], v[6:7], v[6:7], v[4:5]
	v_mov_b32_e32 v6, v17
	v_mov_b32_e32 v7, v13
	v_pk_fma_f32 v[22:23], v[6:7], v[6:7], v[4:5]
	v_add_f32_e32 v22, v22, v23
	v_mov_b32_e32 v26, v133
	v_mov_b32_e32 v27, v137
	v_mov_b32_e32 v24, v132
	v_mov_b32_e32 v25, v136
	v_pk_mul_f32 v[26:27], v[26:27], v[26:27]
	s_nop 0
	v_pk_fma_f32 v[24:25], v[24:25], v[24:25], v[26:27]
	v_mov_b32_e32 v26, v134
	v_mov_b32_e32 v27, v138
	v_pk_fma_f32 v[24:25], v[26:27], v[26:27], v[24:25]
	v_mov_b32_e32 v26, v135
	v_mov_b32_e32 v27, v139
	v_pk_fma_f32 v[24:25], v[26:27], v[26:27], v[24:25]
	v_add_f32_e32 v22, v22, v24
	v_add_f32_e32 v24, v22, v25
	v_and_b32_e32 v18, 64, v219
	v_add_u32_e32 v18, 64, v18
	v_mov_b32_e32 v19, v24
	s_nop 1
	v_permlane32_swap_b32_e32 v19, v24
	s_waitcnt lgkmcnt(0)
	v_add_f32_e32 v19, v24, v19
	s_nop 1
	v_mov_b32_e32 v24, v19
	s_nop 1
	v_permlane16_swap_b32_e32 v24, v19
	s_waitcnt lgkmcnt(0)
	v_add_f32_e32 v19, v19, v24
	s_nop 1
	s_nop 1
	v_mov_b32_dpp v24, v19 row_ror:8 row_mask:0xf bank_mask:0xf
	s_waitcnt lgkmcnt(0)
	v_add_f32_e32 v19, v19, v24
	s_nop 1
	s_nop 1
	v_mov_b32_dpp v24, v19 row_half_mirror row_mask:0xf bank_mask:0xf
	s_waitcnt lgkmcnt(0)
	v_add_f32_e32 v19, v19, v24
	s_nop 1
	s_nop 1
	v_mov_b32_dpp v24, v19 quad_perm:[2,3,0,1] row_mask:0xf bank_mask:0xf
	s_waitcnt lgkmcnt(0)
	v_add_f32_e32 v19, v19, v24
	s_nop 1
	s_nop 1
	v_mov_b32_dpp v18, v19 quad_perm:[1,0,3,2] row_mask:0xf bank_mask:0xf
	v_lshl_add_u64 v[24:25], s[10:11], 0, v[20:21]
	s_waitcnt lgkmcnt(0)
	v_add_f32_e32 v18, v19, v18
	v_mov_b32_e32 v19, 0x358637bd
	v_fmamk_f32 v18, v18, 0x3a800000, v19
	v_cmp_gt_f32_e32 vcc, s2, v18
	v_mul_f32_e32 v19, 0x4b800000, v18
	s_nop 1
	v_cndmask_b32_e32 v18, v18, v19, vcc
	v_rsq_f32_e32 v18, v18
	s_nop 1
	v_mul_f32_e32 v19, 0x45800000, v18
	s_nop 1
	v_cndmask_b32_e32 v18, v18, v19, vcc
	v_pk_mul_f32 v[14:15], v[14:15], v[18:19] op_sel_hi:[1,0]
	v_pk_mul_f32 v[14:15], v[140:141], v[14:15]
	v_pk_mul_f32 v[16:17], v[16:17], v[18:19] op_sel_hi:[1,0]
	v_pk_mul_f32 v[10:11], v[10:11], v[18:19] op_sel_hi:[1,0]
	v_pk_mul_f32 v[16:17], v[142:143], v[16:17]
	v_pk_mul_f32 v[12:13], v[12:13], v[18:19] op_sel_hi:[1,0]
	v_pk_mul_f32 v[6:7], v[132:133], v[18:19] op_sel_hi:[1,0]
	v_pk_mul_f32 v[8:9], v[134:135], v[18:19] op_sel_hi:[1,0]
	v_pk_mul_f32 v[2:3], v[136:137], v[18:19] op_sel_hi:[1,0]
	v_pk_mul_f32 v[4:5], v[138:139], v[18:19] op_sel_hi:[1,0]
	v_pk_add_f32 v[26:27], v[160:161], 1.0 op_sel_hi:[1,0]
	s_nop 0
	v_pk_fma_f32 v[14:15], v[26:27], v[14:15], v[156:157]
	v_pk_add_f32 v[26:27], v[162:163], 1.0 op_sel_hi:[1,0]
	s_nop 0
	v_pk_fma_f32 v[26:27], v[26:27], v[16:17], v[158:159]
	v_cvt_pk_bf16_f32 v16, v14, v15
	v_lshlrev_b32_e32 v14, 1, v38
	v_mov_b32_e32 v15, v199
	v_cvt_pk_bf16_f32 v17, v26, v27
	v_lshl_add_u64 v[14:15], v[24:25], 0, v[14:15]
	global_store_dwordx2 v[14:15], v[16:17], off
	v_pk_mul_f32 v[10:11], v[168:169], v[10:11]
	v_pk_mul_f32 v[12:13], v[170:171], v[12:13]
	v_pk_add_f32 v[16:17], v[176:177], 1.0 op_sel_hi:[1,0]
	s_nop 0
	v_pk_fma_f32 v[10:11], v[16:17], v[10:11], v[172:173]
	v_pk_add_f32 v[16:17], v[178:179], 1.0 op_sel_hi:[1,0]
	v_cvt_pk_bf16_f32 v10, v10, v11
	v_pk_fma_f32 v[12:13], v[16:17], v[12:13], v[174:175]
	v_cvt_pk_bf16_f32 v11, v12, v13
	global_store_dwordx2 v[14:15], v[10:11], off offset:512
	v_pk_mul_f32 v[6:7], v[184:185], v[6:7]
	v_pk_mul_f32 v[8:9], v[186:187], v[8:9]
	v_pk_add_f32 v[10:11], v[192:193], 1.0 op_sel_hi:[1,0]
	s_nop 0
	v_pk_fma_f32 v[6:7], v[6:7], v[10:11], v[188:189]
	v_pk_add_f32 v[10:11], v[194:195], 1.0 op_sel_hi:[1,0]
	v_cvt_pk_bf16_f32 v6, v6, v7
	v_pk_fma_f32 v[8:9], v[8:9], v[10:11], v[190:191]
	s_nop 0
	v_cvt_pk_bf16_f32 v7, v8, v9
	global_store_dwordx2 v[14:15], v[6:7], off offset:1024
	v_pk_mul_f32 v[2:3], v[2:3], v[200:201]
	v_pk_mul_f32 v[4:5], v[4:5], v[202:203]
	v_pk_add_f32 v[6:7], v[224:225], 1.0 op_sel_hi:[1,0]
	s_nop 0
	v_pk_fma_f32 v[2:3], v[2:3], v[6:7], v[204:205]
	v_pk_add_f32 v[6:7], v[226:227], 1.0 op_sel_hi:[1,0]
	v_cvt_pk_bf16_f32 v2, v2, v3
	v_pk_fma_f32 v[4:5], v[4:5], v[6:7], v[206:207]
	s_nop 0
	v_cvt_pk_bf16_f32 v3, v4, v5
	global_store_dwordx2 v[14:15], v[2:3], off offset:1536
	v_mov_b32_e32 v8, v202
	v_mov_b32_e32 v9, v203
	v_mov_b32_e32 v10, v204
	v_mov_b32_e32 v11, v205
	v_mov_b32_e32 v21, v225
	v_mov_b32_e32 v25, v189
	v_mov_b32_e32 v33, v177
	v_mov_b32_e32 v198, v196

; DI unsigned pack2(float lo, float hi) { f32x2 v; v.x = lo; v.y = hi; return __builtin_bit_cast(unsigned, __builtin_convertvector(v, hwbf2)); }
; DI float wave_sum(float v) {
; #pragma unroll
;   for (int o = 32; o > 0; o >>= 1) v += __shfl_xor(v, o);
;   return v;
; }
; DI void norm_rows(KP p, int l, int which, int u, const float* xlat, const float* xctx) {
;     ...
;   f32x4 v[4];
;   float ss = 0;
; #pragma unroll
;   for (int j = 0; j < 4; ++j) {
;     v[j] = *(const f32x4*)(xr + 4 * (lane + 64 * j));
;     ss += v[j].x * v[j].x + v[j].y * v[j].y + v[j].z * v[j].z + v[j].w * v[j].w;
;   }
;   ss = wave_sum(ss);
;   const float rstd = rsqrtf(ss * (1.f / 1024.f) + EPS);
;   u16* H = (u16*)(p->ws + OFF_H) + (size_t)row * 1024;
; #pragma unroll
;   for (int j = 0; j < 4; ++j) {
;     const int c0 = 4 * (lane + 64 * j);
;     f32x4 gg = *(const f32x4*)(g + c0), sh = *(const f32x4*)(mods + c0), sc = *(const f32x4*)(mods + 1024 + c0);
;     float o0 = v[j].x * rstd * gg.x * (1.f + sc.x) + sh.x;
;     float o1 = v[j].y * rstd * gg.y * (1.f + sc.y) + sh.y;
;     float o2 = v[j].z * rstd * gg.z * (1.f + sc.z) + sh.z;
;     float o3 = v[j].w * rstd * gg.w * (1.f + sc.w) + sh.w;
;     *(u32x2*)(H + c0) = mk2(pack2(o0, o1), pack2(o2, o3));
;   }
.LBB0_1855:
	s_or_b64 exec, exec, s[14:15]
	v_lshlrev_b32_e32 v4, 2, v4
	v_and_b32_e32 v38, 0xfc, v4
	v_lshlrev_b32_e32 v198, 2, v38
	v_lshl_add_u64 v[2:3], v[2:3], 0, v[198:199]
	s_load_dwordx2 s[14:15], s[12:13], 0x130
	v_min_i32_e32 v5, 0x4000, v24
	s_load_dwordx2 s[12:13], s[12:13], 0x38
	global_load_dwordx4 v[14:17], v[2:3], off
	global_load_dwordx4 v[10:13], v[2:3], off offset:1024
	v_ashrrev_i32_e32 v5, 12, v5
	v_readlane_b32 s16, v255, 35
	v_lshlrev_b64 v[24:25], 11, v[24:25]
	s_waitcnt lgkmcnt(0)
	v_lshl_add_u64 v[24:25], s[14:15], 0, v[24:25]
	v_add_u32_e32 v5, s16, v5
	v_mul_hi_i32_i24_e32 v19, 0x6000, v5
	v_mul_i32_i24_e32 v18, 0x6000, v5
	s_mov_b64 s[82:83], 0xe823000
	global_load_dwordx4 v[132:135], v[2:3], off offset:2048
	s_nop 0
	global_load_dwordx4 v[136:139], v[2:3], off offset:3072
	v_lshl_add_u64 v[140:141], s[14:15], 0, v[18:19]
	v_lshl_add_u64 v[142:143], v[140:141], 0, s[82:83]
	s_lshl_b64 s[84:85], s[74:75], 2
	s_mov_b64 s[86:87], 0xe824000
	s_add_u32 s88, s12, s84
	v_lshl_add_u64 v[144:145], v[140:141], 0, s[86:87]
	s_addc_u32 s89, s13, s85
	v_lshl_add_u64 v[146:147], v[142:143], 0, v[198:199]
	v_lshl_add_u64 v[148:149], v[144:145], 0, v[198:199]
	global_load_dwordx4 v[152:155], v[146:147], off
	global_load_dwordx4 v[156:159], v[148:149], off
	global_load_dwordx4 v[160:163], v198, s[88:89]
	s_nop 1
	v_or_b32_e32 v150, 0x400, v198
	v_mov_b32_e32 v151, v199
	v_lshl_add_u64 v[164:165], v[142:143], 0, v[150:151]
	v_lshl_add_u64 v[166:167], v[144:145], 0, v[150:151]
	global_load_dwordx4 v[168:171], v198, s[88:89] offset:1024
	global_load_dwordx4 v[172:175], v[166:167], off
	global_load_dwordx4 v[176:179], v[164:165], off
	v_or_b32_e32 v180, 0x800, v198
	v_mov_b32_e32 v181, v199
	v_lshl_add_u64 v[182:183], v[142:143], 0, v[180:181]
	v_lshl_add_u64 v[184:185], v[144:145], 0, v[180:181]
	global_load_dwordx4 v[188:191], v198, s[88:89] offset:2048
	global_load_dwordx4 v[192:195], v[184:185], off
	global_load_dwordx4 v[200:203], v[182:183], off
	global_load_dwordx4 v[204:207], v198, s[88:89] offset:3072
	v_or_b32_e32 v186, 0xc00, v198
	v_mov_b32_e32 v187, v199
	v_lshl_add_u64 v[196:197], v[142:143], 0, v[186:187]
	v_lshl_add_u64 v[208:209], v[144:145], 0, v[186:187]
	global_load_dwordx4 v[224:227], v[196:197], off
	global_load_dwordx4 v[236:239], v[208:209], off
	s_waitcnt vmcnt(0)
	v_mov_b32_e32 v6, v15
	v_mov_b32_e32 v7, v11
	v_mov_b32_e32 v4, v14
	v_mov_b32_e32 v5, v10
	v_pk_mul_f32 v[6:7], v[6:7], v[6:7]
	s_nop 0
	v_pk_fma_f32 v[4:5], v[4:5], v[4:5], v[6:7]
	v_mov_b32_e32 v6, v16
	v_mov_b32_e32 v7, v12
	v_pk_fma_f32 v[4:5], v[6:7], v[6:7], v[4:5]
	v_mov_b32_e32 v6, v17
	v_mov_b32_e32 v7, v13
	v_pk_fma_f32 v[20:21], v[6:7], v[6:7], v[4:5]
	v_add_f32_e32 v20, v20, v21
	v_and_b32_e32 v21, 64, v219
	v_add_u32_e32 v21, 64, v21
	v_mov_b32_e32 v26, v133
	v_mov_b32_e32 v27, v137
	v_mov_b32_e32 v22, v132
	v_mov_b32_e32 v23, v136
	v_pk_mul_f32 v[26:27], v[26:27], v[26:27]
	s_nop 0
	v_pk_fma_f32 v[22:23], v[22:23], v[22:23], v[26:27]
	v_mov_b32_e32 v26, v134
	v_mov_b32_e32 v27, v138
	v_pk_fma_f32 v[22:23], v[26:27], v[26:27], v[22:23]
	v_mov_b32_e32 v26, v135
	v_mov_b32_e32 v27, v139
	v_pk_fma_f32 v[22:23], v[26:27], v[26:27], v[22:23]
	v_add_f32_e32 v20, v20, v22
	v_add_f32_e32 v20, v20, v23
	v_mov_b32_e32 v26, v20
	s_nop 1
	v_permlane32_swap_b32_e32 v26, v20
	s_waitcnt lgkmcnt(0)
	v_add_f32_e32 v20, v20, v26
	v_mov_b32_e32 v26, v20
	s_nop 1
	v_permlane16_swap_b32_e32 v26, v20
	s_waitcnt lgkmcnt(0)
	v_add_f32_e32 v20, v20, v26
	s_mov_b32 s16, 0x800000
	s_nop 1
	v_mov_b32_dpp v26, v20 row_ror:8 row_mask:0xf bank_mask:0xf
	s_waitcnt lgkmcnt(0)
	v_add_f32_e32 v20, v20, v26
	s_nop 1
	s_nop 1
	v_mov_b32_dpp v26, v20 row_half_mirror row_mask:0xf bank_mask:0xf
	s_waitcnt lgkmcnt(0)
	v_add_f32_e32 v20, v20, v26
	s_nop 1
	s_nop 1
	v_mov_b32_dpp v26, v20 quad_perm:[2,3,0,1] row_mask:0xf bank_mask:0xf
	s_waitcnt lgkmcnt(0)
	v_add_f32_e32 v20, v20, v26
	s_nop 1
	v_mov_b32_dpp v21, v20 quad_perm:[1,0,3,2] row_mask:0xf bank_mask:0xf
	s_waitcnt lgkmcnt(0)
	v_add_f32_e32 v20, v20, v21
	v_mov_b32_e32 v21, 0x358637bd
	v_fmamk_f32 v20, v20, 0x3a800000, v21
	v_cmp_gt_f32_e32 vcc, s16, v20
	v_mul_f32_e32 v21, 0x4b800000, v20
	s_nop 0
	v_cndmask_b32_e32 v20, v20, v21, vcc
	v_rsq_f32_e32 v20, v20
	s_nop 0
	v_mul_f32_e32 v21, 0x45800000, v20
	v_cndmask_b32_e32 v20, v20, v21, vcc
	v_pk_mul_f32 v[14:15], v[14:15], v[20:21] op_sel_hi:[1,0]
	v_pk_mul_f32 v[16:17], v[16:17], v[20:21] op_sel_hi:[1,0]
	v_pk_mul_f32 v[10:11], v[10:11], v[20:21] op_sel_hi:[1,0]
	v_pk_mul_f32 v[12:13], v[12:13], v[20:21] op_sel_hi:[1,0]
	v_pk_mul_f32 v[6:7], v[132:133], v[20:21] op_sel_hi:[1,0]
	v_pk_mul_f32 v[8:9], v[134:135], v[20:21] op_sel_hi:[1,0]
	v_pk_mul_f32 v[2:3], v[136:137], v[20:21] op_sel_hi:[1,0]
	v_pk_mul_f32 v[4:5], v[138:139], v[20:21] op_sel_hi:[1,0]
	v_pk_mul_f32 v[14:15], v[160:161], v[14:15]
	v_pk_add_f32 v[26:27], v[156:157], 1.0 op_sel_hi:[1,0]
	v_pk_mul_f32 v[16:17], v[162:163], v[16:17]
	v_pk_fma_f32 v[14:15], v[26:27], v[14:15], v[152:153]
	v_pk_add_f32 v[26:27], v[158:159], 1.0 op_sel_hi:[1,0]
	s_nop 0
	v_pk_fma_f32 v[26:27], v[26:27], v[16:17], v[154:155]
	v_cvt_pk_bf16_f32 v16, v14, v15
	v_lshlrev_b32_e32 v14, 1, v38
	v_mov_b32_e32 v15, v199
	v_cvt_pk_bf16_f32 v17, v26, v27
	v_lshl_add_u64 v[14:15], v[24:25], 0, v[14:15]
	global_store_dwordx2 v[14:15], v[16:17], off
	v_pk_mul_f32 v[10:11], v[168:169], v[10:11]
	v_pk_add_f32 v[16:17], v[172:173], 1.0 op_sel_hi:[1,0]
	v_pk_mul_f32 v[12:13], v[170:171], v[12:13]
	v_pk_fma_f32 v[10:11], v[16:17], v[10:11], v[176:177]
	v_pk_add_f32 v[16:17], v[174:175], 1.0 op_sel_hi:[1,0]
	v_cvt_pk_bf16_f32 v10, v10, v11
	v_pk_fma_f32 v[12:13], v[16:17], v[12:13], v[178:179]
	v_cvt_pk_bf16_f32 v11, v12, v13
	global_store_dwordx2 v[14:15], v[10:11], off offset:512
	v_pk_mul_f32 v[6:7], v[188:189], v[6:7]
	v_pk_add_f32 v[10:11], v[192:193], 1.0 op_sel_hi:[1,0]
	v_pk_mul_f32 v[8:9], v[190:191], v[8:9]
	v_pk_fma_f32 v[6:7], v[6:7], v[10:11], v[200:201]
	v_pk_add_f32 v[10:11], v[194:195], 1.0 op_sel_hi:[1,0]
	v_cvt_pk_bf16_f32 v6, v6, v7
	v_pk_fma_f32 v[8:9], v[8:9], v[10:11], v[202:203]
	s_nop 0
	v_cvt_pk_bf16_f32 v7, v8, v9
	global_store_dwordx2 v[14:15], v[6:7], off offset:1024
	v_pk_mul_f32 v[2:3], v[2:3], v[204:205]
	v_pk_mul_f32 v[4:5], v[4:5], v[206:207]
	v_pk_add_f32 v[6:7], v[236:237], 1.0 op_sel_hi:[1,0]
	s_nop 0
	v_pk_fma_f32 v[2:3], v[2:3], v[6:7], v[224:225]
	v_pk_add_f32 v[6:7], v[238:239], 1.0 op_sel_hi:[1,0]
	v_cvt_pk_bf16_f32 v2, v2, v3
	v_pk_fma_f32 v[4:5], v[4:5], v[6:7], v[226:227]
	s_nop 0
	v_cvt_pk_bf16_f32 v3, v4, v5
	global_store_dwordx2 v[14:15], v[2:3], off offset:1536
	v_mov_b32_e32 v8, v206
	v_mov_b32_e32 v9, v207
	v_mov_b32_e32 v10, v224
	v_mov_b32_e32 v11, v225
	v_mov_b32_e32 v25, v201
	v_mov_b32_e32 v33, v173
	v_mov_b32_e32 v198, v186
